# combined variant plus MLA K fragment reads fed through the QK MFMA gaps
# baseline (speedup 1.0000x reference)
.LBB0_543:
	ds_read_b128 v[32:35], v105
	ds_read_b128 v[48:51], v105 offset:6656
	ds_read_b128 v[132:135], v105 offset:32
	ds_read_b128 v[136:139], v105 offset:6688
	s_waitcnt lgkmcnt(3)
	v_mfma_f32_32x32x16_bf16 v[32:47], v[32:35], v[64:67], 0
	ds_read_b128 v[140:143], v105 offset:64
	s_waitcnt lgkmcnt(3)
	v_mfma_f32_32x32x16_bf16 v[48:63], v[48:51], v[64:67], 0
	ds_read_b128 v[152:155], v105 offset:6720
	s_waitcnt lgkmcnt(3)
	v_mfma_f32_32x32x16_bf16 v[32:47], v[132:135], v[68:71], v[32:47]
	ds_read_b128 v[146:149], v105 offset:96
	s_waitcnt lgkmcnt(3)
	v_mfma_f32_32x32x16_bf16 v[48:63], v[136:139], v[68:71], v[48:63]
	ds_read_b128 v[156:159], v105 offset:6752
	s_waitcnt lgkmcnt(3)
	v_mfma_f32_32x32x16_bf16 v[32:47], v[140:143], v[72:75], v[32:47]
	ds_read_b128 v[160:163], v105 offset:128
	s_waitcnt lgkmcnt(3)
	v_mfma_f32_32x32x16_bf16 v[48:63], v[152:155], v[72:75], v[48:63]
	ds_read_b128 v[168:171], v105 offset:6784
	s_waitcnt lgkmcnt(3)
	v_mfma_f32_32x32x16_bf16 v[32:47], v[146:149], v[76:79], v[32:47]
	ds_read_b128 v[164:167], v105 offset:160
	s_waitcnt lgkmcnt(3)
	v_mfma_f32_32x32x16_bf16 v[48:63], v[156:159], v[76:79], v[48:63]
	ds_read_b128 v[172:175], v105 offset:6816
	s_waitcnt lgkmcnt(3)
	v_mfma_f32_32x32x16_bf16 v[32:47], v[160:163], v[80:83], v[32:47]
	s_waitcnt lgkmcnt(2)
	v_mfma_f32_32x32x16_bf16 v[48:63], v[168:171], v[80:83], v[48:63]
	s_waitcnt lgkmcnt(1)
	v_mfma_f32_32x32x16_bf16 v[32:47], v[164:167], v[84:87], v[32:47]
	s_waitcnt lgkmcnt(0)
	v_mfma_f32_32x32x16_bf16 v[48:63], v[172:175], v[84:87], v[48:63]
	s_nop 9
	v_exp_f32_e32 v121, v32
	v_exp_f32_e32 v125, v33
	v_exp_f32_e32 v126, v34
	v_exp_f32_e32 v127, v35
	v_exp_f32_e32 v131, v36
	v_exp_f32_e32 v132, v37
	v_exp_f32_e32 v133, v38
	v_exp_f32_e32 v135, v48
	v_exp_f32_e32 v136, v49
	v_exp_f32_e32 v137, v50
	v_exp_f32_e32 v138, v51
	v_exp_f32_e32 v139, v52
	v_exp_f32_e32 v140, v53
	v_exp_f32_e32 v141, v54
	v_exp_f32_e32 v134, v39
	v_exp_f32_e32 v142, v55
	v_exp_f32_e32 v143, v40
	v_exp_f32_e32 v158, v56
	v_exp_f32_e32 v144, v41
	v_exp_f32_e32 v159, v57
	v_exp_f32_e32 v152, v42
	v_exp_f32_e32 v160, v58
	v_exp_f32_e32 v153, v43
	v_exp_f32_e32 v161, v59
	v_exp_f32_e32 v154, v44
	v_exp_f32_e32 v162, v60
	v_exp_f32_e32 v155, v45
	v_exp_f32_e32 v163, v61
	v_exp_f32_e32 v156, v46
	v_exp_f32_e32 v164, v62
	v_exp_f32_e32 v157, v47
	v_exp_f32_e32 v165, v63
	ds_read_b64_tr_b16 v[32:33], v218 offset:13312
	ds_read_b64_tr_b16 v[34:35], v218 offset:14336
	ds_read_b64_tr_b16 v[38:39], v218 offset:14592
	ds_read_b64_tr_b16 v[36:37], v218 offset:13568
	ds_read_b64_tr_b16 v[40:41], v218 offset:15360
	ds_read_b64_tr_b16 v[42:43], v218 offset:16384
	ds_read_b64_tr_b16 v[46:47], v218 offset:16640
	ds_read_b64_tr_b16 v[44:45], v218 offset:15616
	ds_read_b64_tr_b16 v[48:49], v218 offset:17408
	ds_read_b64_tr_b16 v[50:51], v218 offset:18432
	ds_read_b64_tr_b16 v[54:55], v218 offset:18688
	ds_read_b64_tr_b16 v[52:53], v218 offset:17664
	ds_read_b64_tr_b16 v[56:57], v218 offset:19456
	ds_read_b64_tr_b16 v[58:59], v218 offset:20480
	ds_read_b64_tr_b16 v[62:63], v218 offset:20736
	ds_read_b64_tr_b16 v[60:61], v218 offset:19712
	v_cvt_pk_bf16_f32 v146, v121, v125
	v_cvt_pk_bf16_f32 v147, v126, v127
	v_cvt_pk_bf16_f32 v148, v131, v132
	v_cvt_pk_bf16_f32 v149, v133, v134
	s_add_i32 s13, s12, 1
	s_waitcnt lgkmcnt(14)
	v_mfma_f32_32x32x16_bf16 v[16:31], v[32:35], v[146:149], v[16:31]
	v_cvt_pk_bf16_f32 v32, v135, v136
	v_cvt_pk_bf16_f32 v33, v137, v138
	v_cvt_pk_bf16_f32 v34, v139, v140
	v_cvt_pk_bf16_f32 v35, v141, v142
	s_cmp_ge_u32 s13, s31
	s_waitcnt lgkmcnt(12)
	v_mfma_f32_32x32x16_bf16 v[0:15], v[36:39], v[146:149], v[0:15]
	v_cvt_pk_bf16_f32 v36, v143, v144
	v_cvt_pk_bf16_f32 v37, v152, v153
	v_cvt_pk_bf16_f32 v38, v154, v155
	v_cvt_pk_bf16_f32 v39, v156, v157
	s_waitcnt lgkmcnt(10)
	v_mfma_f32_32x32x16_bf16 v[16:31], v[40:43], v[36:39], v[16:31]
	s_waitcnt lgkmcnt(8)
	v_mfma_f32_32x32x16_bf16 v[0:15], v[44:47], v[36:39], v[0:15]
	s_waitcnt lgkmcnt(6)
	v_mfma_f32_32x32x16_bf16 v[16:31], v[48:51], v[32:35], v[16:31]
	s_waitcnt lgkmcnt(4)
	v_mfma_f32_32x32x16_bf16 v[0:15], v[52:55], v[32:35], v[0:15]
	v_cvt_pk_bf16_f32 v32, v158, v159
	v_cvt_pk_bf16_f32 v33, v160, v161
	v_cvt_pk_bf16_f32 v34, v162, v163
	v_cvt_pk_bf16_f32 v35, v164, v165
	s_waitcnt lgkmcnt(2)
	v_mfma_f32_32x32x16_bf16 v[16:31], v[56:59], v[32:35], v[16:31]
	s_waitcnt lgkmcnt(0)
	v_mfma_f32_32x32x16_bf16 v[0:15], v[60:63], v[32:35], v[0:15]
	s_cbranch_scc1 .LBB0_545
	s_cmp_ge_u32 s11, s31
	s_cbranch_scc1 .Lmla_w0_tail
	s_waitcnt vmcnt(5)
	ds_write_b128 v220, v[96:99] offset:21504
	s_waitcnt vmcnt(4)
	ds_write_b128 v219, v[100:103] offset:34816
	s_waitcnt vmcnt(3)
	ds_write_b64 v129, v[114:115] offset:21632
	s_branch .LBB0_545

.LBB0_547:
	ds_read_b128 v[32:35], v105 offset:21504
	ds_read_b128 v[48:51], v105 offset:28160
	ds_read_b128 v[146:149], v105 offset:21536
	ds_read_b128 v[166:169], v105 offset:28192
	s_waitcnt lgkmcnt(3)
	v_mfma_f32_32x32x16_bf16 v[32:47], v[32:35], v[64:67], 0
	v_add_f32_e32 v226, v121, v125
	v_add_f32_e32 v227, v135, v136
	v_add_f32_e32 v226, v126, v226
	ds_read_b128 v[170:173], v105 offset:21568
	s_waitcnt lgkmcnt(3)
	v_mfma_f32_32x32x16_bf16 v[48:63], v[48:51], v[64:67], 0
	v_add_f32_e32 v227, v137, v227
	v_add_f32_e32 v226, v127, v226
	v_add_f32_e32 v227, v138, v227
	ds_read_b128 v[178:181], v105 offset:28224
	s_waitcnt lgkmcnt(3)
	v_mfma_f32_32x32x16_bf16 v[32:47], v[146:149], v[68:71], v[32:47]
	v_add_f32_e32 v226, v131, v226
	v_add_f32_e32 v227, v139, v227
	v_add_f32_e32 v226, v132, v226
	ds_read_b128 v[174:177], v105 offset:21600
	s_waitcnt lgkmcnt(3)
	v_mfma_f32_32x32x16_bf16 v[48:63], v[166:169], v[68:71], v[48:63]
	v_add_f32_e32 v227, v140, v227
	v_add_f32_e32 v226, v133, v226
	v_add_f32_e32 v227, v141, v227
	ds_read_b128 v[182:185], v105 offset:28256
	s_waitcnt lgkmcnt(3)
	v_mfma_f32_32x32x16_bf16 v[32:47], v[170:173], v[72:75], v[32:47]
	v_add_f32_e32 v226, v134, v226
	v_add_f32_e32 v227, v142, v227
	v_add_f32_e32 v226, v143, v226
	ds_read_b128 v[186:189], v105 offset:21632
	s_waitcnt lgkmcnt(3)
	v_mfma_f32_32x32x16_bf16 v[48:63], v[178:181], v[72:75], v[48:63]
	v_add_f32_e32 v227, v158, v227
	v_add_f32_e32 v226, v144, v226
	v_add_f32_e32 v227, v159, v227
	ds_read_b128 v[194:197], v105 offset:28288
	s_waitcnt lgkmcnt(3)
	v_mfma_f32_32x32x16_bf16 v[32:47], v[174:177], v[76:79], v[32:47]
	v_add_f32_e32 v226, v152, v226
	v_add_f32_e32 v227, v160, v227
	v_add_f32_e32 v226, v153, v226
	ds_read_b128 v[190:193], v105 offset:21664
	s_waitcnt lgkmcnt(3)
	v_mfma_f32_32x32x16_bf16 v[48:63], v[182:185], v[76:79], v[48:63]
	v_add_f32_e32 v227, v161, v227
	v_add_f32_e32 v226, v154, v226
	v_add_f32_e32 v227, v162, v227
	ds_read_b128 v[198:201], v105 offset:28320
	s_waitcnt lgkmcnt(3)
	v_mfma_f32_32x32x16_bf16 v[32:47], v[186:189], v[80:83], v[32:47]
	v_add_f32_e32 v226, v155, v226
	v_add_f32_e32 v227, v163, v227
	v_add_f32_e32 v226, v156, v226
	s_waitcnt lgkmcnt(2)
	v_mfma_f32_32x32x16_bf16 v[48:63], v[194:197], v[80:83], v[48:63]
	v_add_f32_e32 v227, v164, v227
	v_add_f32_e32 v226, v157, v226
	v_add_f32_e32 v227, v165, v227
	s_waitcnt lgkmcnt(1)
	v_mfma_f32_32x32x16_bf16 v[32:47], v[190:193], v[84:87], v[32:47]
	v_add_f32_e32 v226, v226, v227
	s_waitcnt lgkmcnt(0)
	v_mfma_f32_32x32x16_bf16 v[48:63], v[198:201], v[84:87], v[48:63]
	s_nop 9
	v_exp_f32_e32 v32, v32
	v_exp_f32_e32 v33, v33
	v_exp_f32_e32 v34, v34
	v_exp_f32_e32 v35, v35
	v_exp_f32_e32 v36, v36
	v_exp_f32_e32 v37, v37
	v_exp_f32_e32 v38, v38
	v_exp_f32_e32 v48, v48
	v_exp_f32_e32 v49, v49
	v_exp_f32_e32 v50, v50
	v_exp_f32_e32 v51, v51
	v_exp_f32_e32 v52, v52
	v_exp_f32_e32 v53, v53
	v_exp_f32_e32 v54, v54
	v_exp_f32_e32 v39, v39
	v_exp_f32_e32 v55, v55
	v_exp_f32_e32 v40, v40
	v_exp_f32_e32 v56, v56
	v_exp_f32_e32 v41, v41
	v_exp_f32_e32 v57, v57
	v_exp_f32_e32 v42, v42
	v_exp_f32_e32 v58, v58
	v_exp_f32_e32 v43, v43
	v_exp_f32_e32 v59, v59
	v_exp_f32_e32 v44, v44
	v_exp_f32_e32 v60, v60
	v_exp_f32_e32 v45, v45
	v_exp_f32_e32 v61, v61
	v_exp_f32_e32 v46, v46
	v_exp_f32_e32 v62, v62
	v_exp_f32_e32 v47, v47
	v_exp_f32_e32 v63, v63
	ds_read_b64_tr_b16 v[146:147], v218 offset:34816
	ds_read_b64_tr_b16 v[148:149], v218 offset:35840
	ds_read_b64_tr_b16 v[168:169], v218 offset:36096
	ds_read_b64_tr_b16 v[166:167], v218 offset:35072
	ds_read_b64_tr_b16 v[170:171], v218 offset:36864
	ds_read_b64_tr_b16 v[172:173], v218 offset:37888
	ds_read_b64_tr_b16 v[176:177], v218 offset:38144
	ds_read_b64_tr_b16 v[174:175], v218 offset:37120
	ds_read_b64_tr_b16 v[178:179], v218 offset:38912
	ds_read_b64_tr_b16 v[180:181], v218 offset:39936
	ds_read_b64_tr_b16 v[184:185], v218 offset:40192
	ds_read_b64_tr_b16 v[182:183], v218 offset:39168
	ds_read_b64_tr_b16 v[186:187], v218 offset:40960
	ds_read_b64_tr_b16 v[188:189], v218 offset:41984
	ds_read_b64_tr_b16 v[192:193], v218 offset:42240
	ds_read_b64_tr_b16 v[190:191], v218 offset:41216
	v_cvt_pk_bf16_f32 v194, v32, v33
	v_cvt_pk_bf16_f32 v195, v34, v35
	v_cvt_pk_bf16_f32 v196, v36, v37
	v_cvt_pk_bf16_f32 v197, v38, v39
	s_andn2_b64 vcc, exec, s[8:9]
	s_waitcnt lgkmcnt(14)
	v_mfma_f32_32x32x16_bf16 v[16:31], v[146:149], v[194:197], v[16:31]
	v_add_f32_e32 v228, v32, v33
	v_add_f32_e32 v229, v48, v49
	v_add_f32_e32 v228, v34, v228
	v_add_f32_e32 v229, v50, v229
	v_cvt_pk_bf16_f32 v146, v48, v49
	v_cvt_pk_bf16_f32 v147, v50, v51
	v_cvt_pk_bf16_f32 v148, v52, v53
	v_cvt_pk_bf16_f32 v149, v54, v55
	s_waitcnt lgkmcnt(12)
	v_mfma_f32_32x32x16_bf16 v[0:15], v[166:169], v[194:197], v[0:15]
	v_add_f32_e32 v228, v35, v228
	v_add_f32_e32 v229, v51, v229
	v_add_f32_e32 v228, v36, v228
	v_add_f32_e32 v229, v52, v229
	v_cvt_pk_bf16_f32 v166, v40, v41
	v_cvt_pk_bf16_f32 v167, v42, v43
	v_cvt_pk_bf16_f32 v168, v44, v45
	v_cvt_pk_bf16_f32 v169, v46, v47
	s_waitcnt lgkmcnt(10)
	v_mfma_f32_32x32x16_bf16 v[16:31], v[170:173], v[166:169], v[16:31]
	v_add_f32_e32 v228, v37, v228
	v_add_f32_e32 v229, v53, v229
	v_add_f32_e32 v228, v38, v228
	v_add_f32_e32 v229, v54, v229
	s_waitcnt lgkmcnt(8)
	v_mfma_f32_32x32x16_bf16 v[0:15], v[174:177], v[166:169], v[0:15]
	v_add_f32_e32 v228, v39, v228
	v_add_f32_e32 v229, v55, v229
	v_add_f32_e32 v228, v40, v228
	v_add_f32_e32 v229, v56, v229
	s_waitcnt lgkmcnt(6)
	v_mfma_f32_32x32x16_bf16 v[16:31], v[178:181], v[146:149], v[16:31]
	v_add_f32_e32 v228, v41, v228
	v_add_f32_e32 v229, v57, v229
	v_add_f32_e32 v228, v42, v228
	v_add_f32_e32 v229, v58, v229
	s_waitcnt lgkmcnt(4)
	v_mfma_f32_32x32x16_bf16 v[0:15], v[182:185], v[146:149], v[0:15]
	v_add_f32_e32 v228, v43, v228
	v_add_f32_e32 v229, v59, v229
	v_add_f32_e32 v228, v44, v228
	v_add_f32_e32 v229, v60, v229
	v_cvt_pk_bf16_f32 v146, v56, v57
	v_cvt_pk_bf16_f32 v147, v58, v59
	v_cvt_pk_bf16_f32 v148, v60, v61
	v_cvt_pk_bf16_f32 v149, v62, v63
	s_waitcnt lgkmcnt(2)
	v_mfma_f32_32x32x16_bf16 v[16:31], v[186:189], v[146:149], v[16:31]
	v_add_f32_e32 v228, v45, v228
	v_add_f32_e32 v229, v61, v229
	v_add_f32_e32 v228, v46, v228
	v_add_f32_e32 v229, v62, v229
	s_waitcnt lgkmcnt(0)
	v_mfma_f32_32x32x16_bf16 v[0:15], v[190:193], v[146:149], v[0:15]
	v_add_f32_e32 v228, v47, v228
	v_add_f32_e32 v229, v63, v229
	v_add_f32_e32 v228, v228, v229
	s_cbranch_vccnz .LBB0_549
	s_add_i32 s13, s10, 2
	s_cmp_ge_u32 s11, s13
	s_cbranch_scc1 .Lmla_w1_tail
	s_waitcnt vmcnt(5)
	ds_write_b128 v220, v[88:91]
	s_waitcnt vmcnt(4)
	ds_write_b128 v219, v[92:95] offset:13312
	s_waitcnt vmcnt(3)
	ds_write_b64 v129, v[116:117] offset:128
	s_branch .LBB0_549
